# tok0 memory cross-attention: batched row loads; first grid barrier: the 16 per-XCD counter loads in flight together
# speedup vs baseline: 1.0139x; 1.0139x over previous
; #define LAS __attribute__((address_space(3)))
; DI void tok0_mem(ldsp lds, const float* qm, const float* memb, const float* mnw, const float* Wkv, int hm, LAS float* out64, int tid, int wid, int lane) {
;     ...
;     {
;         const int j4 = (tid & 255) * 4, nh = tid >> 8;
;         f32x4 acc = (f32x4){0.f, 0.f, 0.f, 0.f};
; #pragma unroll 16
;         for (int n = nh * 128; n < nh * 128 + 128; ++n) { const float4 m4 = *(const float4*)(memb + (size_t)n * 1024 + j4); const float c = SC[n]; acc[0] += m4.x * c; acc[1] += m4.y * c; acc[2] += m4.z * c; acc[3] += m4.w * c; }
;         *(LAS f32x4*)(MB + nh * 1024 + j4) = acc;
;     }
;     __syncthreads();
; #pragma unroll
;     for (int h2 = 0; h2 < 2; ++h2) { const int j = tid + h2 * 512; U[j] = (MB[j] + MB[1024 + j]) * mnw[j]; }
;     __syncthreads();
.LBB0_111:
	v_lshl_add_u64 v[10:11], v[8:9], 0, s[26:27]
	s_mov_b64 s[98:99], 0x1000
	ds_read_b128 v[136:139], v14
	ds_read_b128 v[140:143], v14 offset:16
	ds_read_b128 v[144:147], v14 offset:32
	ds_read_b128 v[148:151], v14 offset:48
	v_lshl_add_u64 v[120:121], v[10:11], 0, 0
	global_load_dwordx4 v[158:161], v[120:121], off
	v_lshl_add_u64 v[122:123], v[120:121], 0, s[98:99]
	global_load_dwordx4 v[162:165], v[122:123], off
	v_lshl_add_u64 v[120:121], v[122:123], 0, s[98:99]
	global_load_dwordx4 v[166:169], v[120:121], off
	v_lshl_add_u64 v[122:123], v[120:121], 0, s[98:99]
	global_load_dwordx4 v[170:173], v[122:123], off
	v_lshl_add_u64 v[120:121], v[122:123], 0, s[98:99]
	global_load_dwordx4 v[174:177], v[120:121], off
	v_lshl_add_u64 v[122:123], v[120:121], 0, s[98:99]
	global_load_dwordx4 v[178:181], v[122:123], off
	v_lshl_add_u64 v[120:121], v[122:123], 0, s[98:99]
	global_load_dwordx4 v[182:185], v[120:121], off
	v_lshl_add_u64 v[122:123], v[120:121], 0, s[98:99]
	global_load_dwordx4 v[186:189], v[122:123], off
	v_lshl_add_u64 v[120:121], v[122:123], 0, s[98:99]
	global_load_dwordx4 v[190:193], v[120:121], off
	v_lshl_add_u64 v[122:123], v[120:121], 0, s[98:99]
	global_load_dwordx4 v[194:197], v[122:123], off
	v_lshl_add_u64 v[120:121], v[122:123], 0, s[98:99]
	global_load_dwordx4 v[198:201], v[120:121], off
	v_lshl_add_u64 v[122:123], v[120:121], 0, s[98:99]
	global_load_dwordx4 v[202:205], v[122:123], off
	v_lshl_add_u64 v[120:121], v[122:123], 0, s[98:99]
	global_load_dwordx4 v[206:209], v[120:121], off
	v_lshl_add_u64 v[122:123], v[120:121], 0, s[98:99]
	global_load_dwordx4 v[210:213], v[122:123], off
	v_lshl_add_u64 v[120:121], v[122:123], 0, s[98:99]
	global_load_dwordx4 v[214:217], v[120:121], off
	v_lshl_add_u64 v[122:123], v[120:121], 0, s[98:99]
	global_load_dwordx4 v[218:221], v[122:123], off
	s_add_u32 s26, s26, 0x10000
	s_addc_u32 s27, s27, 0
	v_add_u32_e32 v14, 64, v14
	s_waitcnt vmcnt(15) lgkmcnt(3)
	v_pk_fma_f32 v[6:7], v[160:161], v[136:137], v[6:7] op_sel_hi:[1,0,1]
	v_pk_fma_f32 v[4:5], v[158:159], v[136:137], v[4:5] op_sel_hi:[1,0,1]
	s_waitcnt vmcnt(14)
	v_pk_fma_f32 v[6:7], v[164:165], v[136:137], v[6:7] op_sel:[0,1,0]
	v_pk_fma_f32 v[4:5], v[162:163], v[136:137], v[4:5] op_sel:[0,1,0]
	s_waitcnt vmcnt(13)
	v_pk_fma_f32 v[6:7], v[168:169], v[138:139], v[6:7] op_sel_hi:[1,0,1]
	v_pk_fma_f32 v[4:5], v[166:167], v[138:139], v[4:5] op_sel_hi:[1,0,1]
	s_waitcnt vmcnt(12)
	v_pk_fma_f32 v[6:7], v[172:173], v[138:139], v[6:7] op_sel:[0,1,0]
	v_pk_fma_f32 v[4:5], v[170:171], v[138:139], v[4:5] op_sel:[0,1,0]
	s_waitcnt vmcnt(11) lgkmcnt(2)
	v_pk_fma_f32 v[6:7], v[176:177], v[140:141], v[6:7] op_sel_hi:[1,0,1]
	v_pk_fma_f32 v[4:5], v[174:175], v[140:141], v[4:5] op_sel_hi:[1,0,1]
	s_waitcnt vmcnt(10)
	v_pk_fma_f32 v[6:7], v[180:181], v[140:141], v[6:7] op_sel:[0,1,0]
	v_pk_fma_f32 v[4:5], v[178:179], v[140:141], v[4:5] op_sel:[0,1,0]
	s_waitcnt vmcnt(9)
	v_pk_fma_f32 v[6:7], v[184:185], v[142:143], v[6:7] op_sel_hi:[1,0,1]
	v_pk_fma_f32 v[4:5], v[182:183], v[142:143], v[4:5] op_sel_hi:[1,0,1]
	s_waitcnt vmcnt(8)
	v_pk_fma_f32 v[6:7], v[188:189], v[142:143], v[6:7] op_sel:[0,1,0]
	v_pk_fma_f32 v[4:5], v[186:187], v[142:143], v[4:5] op_sel:[0,1,0]
	s_waitcnt vmcnt(7) lgkmcnt(1)
	v_pk_fma_f32 v[6:7], v[192:193], v[144:145], v[6:7] op_sel_hi:[1,0,1]
	v_pk_fma_f32 v[4:5], v[190:191], v[144:145], v[4:5] op_sel_hi:[1,0,1]
	s_waitcnt vmcnt(6)
	v_pk_fma_f32 v[6:7], v[196:197], v[144:145], v[6:7] op_sel:[0,1,0]
	v_pk_fma_f32 v[4:5], v[194:195], v[144:145], v[4:5] op_sel:[0,1,0]
	s_waitcnt vmcnt(5)
	v_pk_fma_f32 v[6:7], v[200:201], v[146:147], v[6:7] op_sel_hi:[1,0,1]
	v_pk_fma_f32 v[4:5], v[198:199], v[146:147], v[4:5] op_sel_hi:[1,0,1]
	s_waitcnt vmcnt(4)
	v_pk_fma_f32 v[6:7], v[204:205], v[146:147], v[6:7] op_sel:[0,1,0]
	v_pk_fma_f32 v[4:5], v[202:203], v[146:147], v[4:5] op_sel:[0,1,0]
	s_waitcnt vmcnt(3) lgkmcnt(0)
	v_pk_fma_f32 v[6:7], v[208:209], v[148:149], v[6:7] op_sel_hi:[1,0,1]
	v_pk_fma_f32 v[4:5], v[206:207], v[148:149], v[4:5] op_sel_hi:[1,0,1]
	s_waitcnt vmcnt(2)
	v_pk_fma_f32 v[6:7], v[212:213], v[148:149], v[6:7] op_sel:[0,1,0]
	v_pk_fma_f32 v[4:5], v[210:211], v[148:149], v[4:5] op_sel:[0,1,0]
	s_waitcnt vmcnt(1)
	v_pk_fma_f32 v[6:7], v[216:217], v[150:151], v[6:7] op_sel_hi:[1,0,1]
	v_pk_fma_f32 v[4:5], v[214:215], v[150:151], v[4:5] op_sel_hi:[1,0,1]
	s_waitcnt vmcnt(0)
	v_pk_fma_f32 v[6:7], v[220:221], v[150:151], v[6:7] op_sel:[0,1,0]
	v_pk_fma_f32 v[4:5], v[218:219], v[150:151], v[4:5] op_sel:[0,1,0]
	s_cmp_eq_u32 s26, 0x80000
	s_cbranch_scc0 .LBB0_111
	ds_write_b128 v101, v[4:7] offset:6144
	s_waitcnt lgkmcnt(0)
	s_barrier
	ds_read2st64_b32 v[0:1], v13 offset0:24 offset1:32
	ds_read2st64_b32 v[2:3], v13 offset0:40 offset1:48
	s_and_b32 s0, s19, 3
	s_lshl_b32 s0, s0, 8
	v_mov_b32_e32 v4, 0
	v_lshl_add_u64 v[8:9], v[88:89], 0, s[0:1]
	s_waitcnt lgkmcnt(0)
	v_add_f32_e32 v0, v0, v2
	global_load_dword v2, v[90:91], off
	v_add_f32_e32 v1, v1, v3
	s_mov_b64 s[26:27], 0
	v_mov_b32_e32 v14, v105
	v_mov_b32_e32 v5, v4
	v_mov_b32_e32 v6, v4
	v_mov_b32_e32 v7, v4
	s_waitcnt vmcnt(0)
	v_mul_f32_e32 v0, v0, v2
	global_load_dword v2, v[82:83], off offset:2048
	s_waitcnt vmcnt(0)
	v_mul_f32_e32 v1, v1, v2
	ds_write2st64_b32 v13, v0, v1 offset1:8
	s_waitcnt lgkmcnt(0)
	s_barrier
; #define LAS __attribute__((address_space(3)))
; DI void tok0_mem(ldsp lds, const float* qm, const float* memb, const float* mnw, const float* Wkv, int hm, LAS float* out64, int tid, int wid, int lane) {
;     ...
;     {
;         const int d4 = tid & 15, js = tid >> 4;
;         f32x4 o = (f32x4){0.f, 0.f, 0.f, 0.f};
; #pragma unroll 16
;         for (int j = js * 32; j < js * 32 + 32; ++j) { const float4 w4 = *(const float4*)(Wkv + (size_t)j * 512 + 256 + hm * 64 + d4 * 4); const float m = U[j]; o[0] += w4.x * m; o[1] += w4.y * m; o[2] += w4.z * m; o[3] += w4.w * m; }
;         *(LAS f32x4*)(PO + js * 64 + d4 * 4) = o;
;     }
;     __syncthreads();
;     if (tid < 64) { float t = 0.f;
; #pragma unroll
;         for (int js = 0; js < 32; ++js) t += PO[js * 64 + tid];
;         out64[tid] = t; }
.LBB0_113:
	v_lshl_add_u64 v[10:11], v[8:9], 0, s[26:27]
	s_mov_b64 s[98:99], 0x800
	ds_read_b128 v[136:139], v14
	ds_read_b128 v[140:143], v14 offset:16
	ds_read_b128 v[144:147], v14 offset:32
	ds_read_b128 v[148:151], v14 offset:48
	s_mov_b64 s[100:101], 0x200400
	v_lshl_add_u64 v[120:121], v[10:11], 0, s[100:101]
	global_load_dwordx4 v[158:161], v[120:121], off
	v_lshl_add_u64 v[122:123], v[120:121], 0, s[98:99]
	global_load_dwordx4 v[162:165], v[122:123], off
	v_lshl_add_u64 v[120:121], v[122:123], 0, s[98:99]
	global_load_dwordx4 v[166:169], v[120:121], off
	v_lshl_add_u64 v[122:123], v[120:121], 0, s[98:99]
	global_load_dwordx4 v[170:173], v[122:123], off
	v_lshl_add_u64 v[120:121], v[122:123], 0, s[98:99]
	global_load_dwordx4 v[174:177], v[120:121], off
	v_lshl_add_u64 v[122:123], v[120:121], 0, s[98:99]
	global_load_dwordx4 v[178:181], v[122:123], off
	v_lshl_add_u64 v[120:121], v[122:123], 0, s[98:99]
	global_load_dwordx4 v[182:185], v[120:121], off
	v_lshl_add_u64 v[122:123], v[120:121], 0, s[98:99]
	global_load_dwordx4 v[186:189], v[122:123], off
	v_lshl_add_u64 v[120:121], v[122:123], 0, s[98:99]
	global_load_dwordx4 v[190:193], v[120:121], off
	v_lshl_add_u64 v[122:123], v[120:121], 0, s[98:99]
	global_load_dwordx4 v[194:197], v[122:123], off
	v_lshl_add_u64 v[120:121], v[122:123], 0, s[98:99]
	global_load_dwordx4 v[198:201], v[120:121], off
	v_lshl_add_u64 v[122:123], v[120:121], 0, s[98:99]
	global_load_dwordx4 v[202:205], v[122:123], off
	v_lshl_add_u64 v[120:121], v[122:123], 0, s[98:99]
	global_load_dwordx4 v[206:209], v[120:121], off
	v_lshl_add_u64 v[122:123], v[120:121], 0, s[98:99]
	global_load_dwordx4 v[210:213], v[122:123], off
	v_lshl_add_u64 v[120:121], v[122:123], 0, s[98:99]
	global_load_dwordx4 v[214:217], v[120:121], off
	v_lshl_add_u64 v[122:123], v[120:121], 0, s[98:99]
	global_load_dwordx4 v[218:221], v[122:123], off
	s_add_u32 s26, s26, 0x8000
	s_addc_u32 s27, s27, 0
	v_add_u32_e32 v14, 64, v14
	s_waitcnt vmcnt(15) lgkmcnt(3)
	v_pk_fma_f32 v[6:7], v[160:161], v[136:137], v[6:7] op_sel_hi:[1,0,1]
	v_pk_fma_f32 v[4:5], v[158:159], v[136:137], v[4:5] op_sel_hi:[1,0,1]
	s_waitcnt vmcnt(14)
	v_pk_fma_f32 v[6:7], v[164:165], v[136:137], v[6:7] op_sel:[0,1,0]
	v_pk_fma_f32 v[4:5], v[162:163], v[136:137], v[4:5] op_sel:[0,1,0]
	s_waitcnt vmcnt(13)
	v_pk_fma_f32 v[6:7], v[168:169], v[138:139], v[6:7] op_sel_hi:[1,0,1]
	v_pk_fma_f32 v[4:5], v[166:167], v[138:139], v[4:5] op_sel_hi:[1,0,1]
	s_waitcnt vmcnt(12)
	v_pk_fma_f32 v[6:7], v[172:173], v[138:139], v[6:7] op_sel:[0,1,0]
	v_pk_fma_f32 v[4:5], v[170:171], v[138:139], v[4:5] op_sel:[0,1,0]
	s_waitcnt vmcnt(11) lgkmcnt(2)
	v_pk_fma_f32 v[6:7], v[176:177], v[140:141], v[6:7] op_sel_hi:[1,0,1]
	v_pk_fma_f32 v[4:5], v[174:175], v[140:141], v[4:5] op_sel_hi:[1,0,1]
	s_waitcnt vmcnt(10)
	v_pk_fma_f32 v[6:7], v[180:181], v[140:141], v[6:7] op_sel:[0,1,0]
	v_pk_fma_f32 v[4:5], v[178:179], v[140:141], v[4:5] op_sel:[0,1,0]
	s_waitcnt vmcnt(9)
	v_pk_fma_f32 v[6:7], v[184:185], v[142:143], v[6:7] op_sel_hi:[1,0,1]
	v_pk_fma_f32 v[4:5], v[182:183], v[142:143], v[4:5] op_sel_hi:[1,0,1]
	s_waitcnt vmcnt(8)
	v_pk_fma_f32 v[6:7], v[188:189], v[142:143], v[6:7] op_sel:[0,1,0]
	v_pk_fma_f32 v[4:5], v[186:187], v[142:143], v[4:5] op_sel:[0,1,0]
	s_waitcnt vmcnt(7) lgkmcnt(1)
	v_pk_fma_f32 v[6:7], v[192:193], v[144:145], v[6:7] op_sel_hi:[1,0,1]
	v_pk_fma_f32 v[4:5], v[190:191], v[144:145], v[4:5] op_sel_hi:[1,0,1]
	s_waitcnt vmcnt(6)
	v_pk_fma_f32 v[6:7], v[196:197], v[144:145], v[6:7] op_sel:[0,1,0]
	v_pk_fma_f32 v[4:5], v[194:195], v[144:145], v[4:5] op_sel:[0,1,0]
	s_waitcnt vmcnt(5)
	v_pk_fma_f32 v[6:7], v[200:201], v[146:147], v[6:7] op_sel_hi:[1,0,1]
	v_pk_fma_f32 v[4:5], v[198:199], v[146:147], v[4:5] op_sel_hi:[1,0,1]
	s_waitcnt vmcnt(4)
	v_pk_fma_f32 v[6:7], v[204:205], v[146:147], v[6:7] op_sel:[0,1,0]
	v_pk_fma_f32 v[4:5], v[202:203], v[146:147], v[4:5] op_sel:[0,1,0]
	s_waitcnt vmcnt(3) lgkmcnt(0)
	v_pk_fma_f32 v[6:7], v[208:209], v[148:149], v[6:7] op_sel_hi:[1,0,1]
	v_pk_fma_f32 v[4:5], v[206:207], v[148:149], v[4:5] op_sel_hi:[1,0,1]
	s_waitcnt vmcnt(2)
	v_pk_fma_f32 v[6:7], v[212:213], v[148:149], v[6:7] op_sel:[0,1,0]
	v_pk_fma_f32 v[4:5], v[210:211], v[148:149], v[4:5] op_sel:[0,1,0]
	s_waitcnt vmcnt(1)
	v_pk_fma_f32 v[6:7], v[216:217], v[150:151], v[6:7] op_sel_hi:[1,0,1]
	v_pk_fma_f32 v[4:5], v[214:215], v[150:151], v[4:5] op_sel_hi:[1,0,1]
	s_waitcnt vmcnt(0)
	v_pk_fma_f32 v[6:7], v[220:221], v[150:151], v[6:7] op_sel:[0,1,0]
	v_pk_fma_f32 v[4:5], v[218:219], v[150:151], v[4:5] op_sel:[0,1,0]
	s_cmp_eq_u32 s26, 0x10000
	s_cbranch_scc0 .LBB0_113
	ds_write_b128 v107, v[4:7] offset:14592
	s_waitcnt lgkmcnt(0)
	s_barrier
	s_and_saveexec_b64 s[26:27], s[38:39]
	s_cbranch_execz .LBB0_116
	ds_read2st64_b32 v[0:1], v13 offset0:57 offset1:58
	s_waitcnt lgkmcnt(0)
	v_add_f32_e32 v0, 0, v0
	v_add_f32_e32 v2, v0, v1
	ds_read2st64_b32 v[0:1], v13 offset0:59 offset1:60
	s_waitcnt lgkmcnt(0)
	v_add_f32_e32 v0, v2, v0
	v_add_f32_e32 v2, v0, v1
	ds_read2st64_b32 v[0:1], v13 offset0:61 offset1:62
	s_waitcnt lgkmcnt(0)
	v_add_f32_e32 v0, v2, v0
	v_add_f32_e32 v2, v0, v1
	ds_read2st64_b32 v[0:1], v13 offset0:63 offset1:64
	s_waitcnt lgkmcnt(0)
	v_add_f32_e32 v0, v2, v0
	v_add_f32_e32 v2, v0, v1
	ds_read2st64_b32 v[0:1], v13 offset0:65 offset1:66
	s_waitcnt lgkmcnt(0)
	v_add_f32_e32 v0, v2, v0
	v_add_f32_e32 v2, v0, v1
	ds_read2st64_b32 v[0:1], v13 offset0:67 offset1:68
	s_waitcnt lgkmcnt(0)
	v_add_f32_e32 v0, v2, v0
	v_add_f32_e32 v2, v0, v1
	ds_read2st64_b32 v[0:1], v13 offset0:69 offset1:70
	s_waitcnt lgkmcnt(0)
	v_add_f32_e32 v0, v2, v0
	v_add_f32_e32 v2, v0, v1
	ds_read2st64_b32 v[0:1], v13 offset0:71 offset1:72
	s_waitcnt lgkmcnt(0)
	v_add_f32_e32 v0, v2, v0
	v_add_f32_e32 v2, v0, v1
	ds_read2st64_b32 v[0:1], v13 offset0:73 offset1:74
	s_waitcnt lgkmcnt(0)
	v_add_f32_e32 v0, v2, v0
	v_add_f32_e32 v2, v0, v1
	ds_read2st64_b32 v[0:1], v13 offset0:75 offset1:76
	s_waitcnt lgkmcnt(0)
	v_add_f32_e32 v0, v2, v0
	v_add_f32_e32 v2, v0, v1
	ds_read2st64_b32 v[0:1], v13 offset0:77 offset1:78
	s_waitcnt lgkmcnt(0)
	v_add_f32_e32 v0, v2, v0
	v_add_f32_e32 v2, v0, v1
	ds_read2st64_b32 v[0:1], v13 offset0:79 offset1:80
	s_waitcnt lgkmcnt(0)
	v_add_f32_e32 v0, v2, v0
	v_add_f32_e32 v2, v0, v1
	ds_read2st64_b32 v[0:1], v13 offset0:81 offset1:82
	s_waitcnt lgkmcnt(0)
	v_add_f32_e32 v0, v2, v0
	v_add_f32_e32 v2, v0, v1
	ds_read2st64_b32 v[0:1], v13 offset0:83 offset1:84
	s_waitcnt lgkmcnt(0)
	v_add_f32_e32 v0, v2, v0
	v_add_f32_e32 v2, v0, v1
	ds_read2st64_b32 v[0:1], v13 offset0:85 offset1:86
	s_waitcnt lgkmcnt(0)
	v_add_f32_e32 v0, v2, v0
	v_add_f32_e32 v2, v0, v1
	ds_read2st64_b32 v[0:1], v13 offset0:87 offset1:88
	s_waitcnt lgkmcnt(0)
	v_add_f32_e32 v0, v2, v0
	v_add_f32_e32 v0, v0, v1
	ds_write_b32 v102, v0

; #define LAS __attribute__((address_space(3)))
; DI void tok0_mem(ldsp lds, const float* qm, const float* memb, const float* mnw, const float* Wkv, int hm, LAS float* out64, int tid, int wid, int lane) {
;     ...
;     {
;         const int j4 = (tid & 255) * 4, nh = tid >> 8;
;         f32x4 acc = (f32x4){0.f, 0.f, 0.f, 0.f};
; #pragma unroll 16
;         for (int n = nh * 128; n < nh * 128 + 128; ++n) { const float4 m4 = *(const float4*)(memb + (size_t)n * 1024 + j4); const float c = SC[n]; acc[0] += m4.x * c; acc[1] += m4.y * c; acc[2] += m4.z * c; acc[3] += m4.w * c; }
;         *(LAS f32x4*)(MB + nh * 1024 + j4) = acc;
;     }
;     __syncthreads();
; #pragma unroll
;     for (int h2 = 0; h2 < 2; ++h2) { const int j = tid + h2 * 512; U[j] = (MB[j] + MB[1024 + j]) * mnw[j]; }
;     __syncthreads();
.LBB0_845:
	v_lshl_add_u64 v[10:11], v[8:9], 0, s[26:27]
	s_mov_b64 s[98:99], 0x1000
	ds_read_b128 v[136:139], v14
	ds_read_b128 v[140:143], v14 offset:16
	ds_read_b128 v[144:147], v14 offset:32
	ds_read_b128 v[148:151], v14 offset:48
	v_lshl_add_u64 v[120:121], v[10:11], 0, 0
	global_load_dwordx4 v[158:161], v[120:121], off
	v_lshl_add_u64 v[122:123], v[120:121], 0, s[98:99]
	global_load_dwordx4 v[162:165], v[122:123], off
	v_lshl_add_u64 v[120:121], v[122:123], 0, s[98:99]
	global_load_dwordx4 v[166:169], v[120:121], off
	v_lshl_add_u64 v[122:123], v[120:121], 0, s[98:99]
	global_load_dwordx4 v[170:173], v[122:123], off
	v_lshl_add_u64 v[120:121], v[122:123], 0, s[98:99]
	global_load_dwordx4 v[174:177], v[120:121], off
	v_lshl_add_u64 v[122:123], v[120:121], 0, s[98:99]
	global_load_dwordx4 v[178:181], v[122:123], off
	v_lshl_add_u64 v[120:121], v[122:123], 0, s[98:99]
	global_load_dwordx4 v[182:185], v[120:121], off
	v_lshl_add_u64 v[122:123], v[120:121], 0, s[98:99]
	global_load_dwordx4 v[186:189], v[122:123], off
	v_lshl_add_u64 v[120:121], v[122:123], 0, s[98:99]
	global_load_dwordx4 v[190:193], v[120:121], off
	v_lshl_add_u64 v[122:123], v[120:121], 0, s[98:99]
	global_load_dwordx4 v[194:197], v[122:123], off
	v_lshl_add_u64 v[120:121], v[122:123], 0, s[98:99]
	global_load_dwordx4 v[198:201], v[120:121], off
	v_lshl_add_u64 v[122:123], v[120:121], 0, s[98:99]
	global_load_dwordx4 v[202:205], v[122:123], off
	v_lshl_add_u64 v[120:121], v[122:123], 0, s[98:99]
	global_load_dwordx4 v[206:209], v[120:121], off
	v_lshl_add_u64 v[122:123], v[120:121], 0, s[98:99]
	global_load_dwordx4 v[210:213], v[122:123], off
	v_lshl_add_u64 v[120:121], v[122:123], 0, s[98:99]
	global_load_dwordx4 v[214:217], v[120:121], off
	v_lshl_add_u64 v[122:123], v[120:121], 0, s[98:99]
	global_load_dwordx4 v[218:221], v[122:123], off
	s_add_u32 s26, s26, 0x10000
	s_addc_u32 s27, s27, 0
	v_add_u32_e32 v14, 64, v14
	s_waitcnt vmcnt(15) lgkmcnt(3)
	v_pk_fma_f32 v[6:7], v[160:161], v[136:137], v[6:7] op_sel_hi:[1,0,1]
	v_pk_fma_f32 v[4:5], v[158:159], v[136:137], v[4:5] op_sel_hi:[1,0,1]
	s_waitcnt vmcnt(14)
	v_pk_fma_f32 v[6:7], v[164:165], v[136:137], v[6:7] op_sel:[0,1,0]
	v_pk_fma_f32 v[4:5], v[162:163], v[136:137], v[4:5] op_sel:[0,1,0]
	s_waitcnt vmcnt(13)
	v_pk_fma_f32 v[6:7], v[168:169], v[138:139], v[6:7] op_sel_hi:[1,0,1]
	v_pk_fma_f32 v[4:5], v[166:167], v[138:139], v[4:5] op_sel_hi:[1,0,1]
	s_waitcnt vmcnt(12)
	v_pk_fma_f32 v[6:7], v[172:173], v[138:139], v[6:7] op_sel:[0,1,0]
	v_pk_fma_f32 v[4:5], v[170:171], v[138:139], v[4:5] op_sel:[0,1,0]
	s_waitcnt vmcnt(11) lgkmcnt(2)
	v_pk_fma_f32 v[6:7], v[176:177], v[140:141], v[6:7] op_sel_hi:[1,0,1]
	v_pk_fma_f32 v[4:5], v[174:175], v[140:141], v[4:5] op_sel_hi:[1,0,1]
	s_waitcnt vmcnt(10)
	v_pk_fma_f32 v[6:7], v[180:181], v[140:141], v[6:7] op_sel:[0,1,0]
	v_pk_fma_f32 v[4:5], v[178:179], v[140:141], v[4:5] op_sel:[0,1,0]
	s_waitcnt vmcnt(9)
	v_pk_fma_f32 v[6:7], v[184:185], v[142:143], v[6:7] op_sel_hi:[1,0,1]
	v_pk_fma_f32 v[4:5], v[182:183], v[142:143], v[4:5] op_sel_hi:[1,0,1]
	s_waitcnt vmcnt(8)
	v_pk_fma_f32 v[6:7], v[188:189], v[142:143], v[6:7] op_sel:[0,1,0]
	v_pk_fma_f32 v[4:5], v[186:187], v[142:143], v[4:5] op_sel:[0,1,0]
	s_waitcnt vmcnt(7) lgkmcnt(1)
	v_pk_fma_f32 v[6:7], v[192:193], v[144:145], v[6:7] op_sel_hi:[1,0,1]
	v_pk_fma_f32 v[4:5], v[190:191], v[144:145], v[4:5] op_sel_hi:[1,0,1]
	s_waitcnt vmcnt(6)
	v_pk_fma_f32 v[6:7], v[196:197], v[144:145], v[6:7] op_sel:[0,1,0]
	v_pk_fma_f32 v[4:5], v[194:195], v[144:145], v[4:5] op_sel:[0,1,0]
	s_waitcnt vmcnt(5)
	v_pk_fma_f32 v[6:7], v[200:201], v[146:147], v[6:7] op_sel_hi:[1,0,1]
	v_pk_fma_f32 v[4:5], v[198:199], v[146:147], v[4:5] op_sel_hi:[1,0,1]
	s_waitcnt vmcnt(4)
	v_pk_fma_f32 v[6:7], v[204:205], v[146:147], v[6:7] op_sel:[0,1,0]
	v_pk_fma_f32 v[4:5], v[202:203], v[146:147], v[4:5] op_sel:[0,1,0]
	s_waitcnt vmcnt(3) lgkmcnt(0)
	v_pk_fma_f32 v[6:7], v[208:209], v[148:149], v[6:7] op_sel_hi:[1,0,1]
	v_pk_fma_f32 v[4:5], v[206:207], v[148:149], v[4:5] op_sel_hi:[1,0,1]
	s_waitcnt vmcnt(2)
	v_pk_fma_f32 v[6:7], v[212:213], v[148:149], v[6:7] op_sel:[0,1,0]
	v_pk_fma_f32 v[4:5], v[210:211], v[148:149], v[4:5] op_sel:[0,1,0]
	s_waitcnt vmcnt(1)
	v_pk_fma_f32 v[6:7], v[216:217], v[150:151], v[6:7] op_sel_hi:[1,0,1]
	v_pk_fma_f32 v[4:5], v[214:215], v[150:151], v[4:5] op_sel_hi:[1,0,1]
	s_waitcnt vmcnt(0)
	v_pk_fma_f32 v[6:7], v[220:221], v[150:151], v[6:7] op_sel:[0,1,0]
	v_pk_fma_f32 v[4:5], v[218:219], v[150:151], v[4:5] op_sel:[0,1,0]
	s_cmp_eq_u32 s26, 0x80000
	s_cbranch_scc0 .LBB0_845
	ds_write_b128 v103, v[4:7] offset:6144
	s_waitcnt lgkmcnt(0)
	s_barrier
	ds_read2st64_b32 v[0:1], v13 offset0:24 offset1:32
	ds_read2st64_b32 v[2:3], v13 offset0:40 offset1:48
	s_and_b32 s0, s35, 3
	s_lshl_b32 s0, s0, 8
	v_mov_b32_e32 v4, 0
	v_lshl_add_u64 v[8:9], v[88:89], 0, s[0:1]
	s_waitcnt lgkmcnt(0)
	v_add_f32_e32 v0, v0, v2
	global_load_dword v2, v[92:93], off
	v_add_f32_e32 v1, v1, v3
	s_mov_b64 s[26:27], 0
	v_mov_b32_e32 v14, v108
	v_mov_b32_e32 v5, v4
	v_mov_b32_e32 v6, v4
	v_mov_b32_e32 v7, v4
	s_movk_i32 s22, 0x1000
	s_movk_i32 s23, 0x3000
	s_waitcnt vmcnt(0)
	v_mul_f32_e32 v0, v0, v2
	global_load_dword v2, v[80:81], off offset:2048
	s_waitcnt vmcnt(0)
	v_mul_f32_e32 v1, v1, v2
	ds_write2st64_b32 v13, v0, v1 offset1:8
	s_waitcnt lgkmcnt(0)
	s_barrier
; #define LAS __attribute__((address_space(3)))
; DI void tok0_mem(ldsp lds, const float* qm, const float* memb, const float* mnw, const float* Wkv, int hm, LAS float* out64, int tid, int wid, int lane) {
;     ...
;     {
;         const int d4 = tid & 15, js = tid >> 4;
;         f32x4 o = (f32x4){0.f, 0.f, 0.f, 0.f};
; #pragma unroll 16
;         for (int j = js * 32; j < js * 32 + 32; ++j) { const float4 w4 = *(const float4*)(Wkv + (size_t)j * 512 + 256 + hm * 64 + d4 * 4); const float m = U[j]; o[0] += w4.x * m; o[1] += w4.y * m; o[2] += w4.z * m; o[3] += w4.w * m; }
;         *(LAS f32x4*)(PO + js * 64 + d4 * 4) = o;
;     }
;     __syncthreads();
;     if (tid < 64) { float t = 0.f;
; #pragma unroll
;         for (int js = 0; js < 32; ++js) t += PO[js * 64 + tid];
;         out64[tid] = t; }
.LBB0_847:
	v_lshl_add_u64 v[10:11], v[8:9], 0, s[26:27]
	s_mov_b64 s[98:99], 0x800
	ds_read_b128 v[136:139], v14
	ds_read_b128 v[140:143], v14 offset:16
	ds_read_b128 v[144:147], v14 offset:32
	ds_read_b128 v[148:151], v14 offset:48
	s_mov_b64 s[100:101], 0x400
	v_lshl_add_u64 v[120:121], v[10:11], 0, s[100:101]
	global_load_dwordx4 v[158:161], v[120:121], off
	v_lshl_add_u64 v[122:123], v[120:121], 0, s[98:99]
	global_load_dwordx4 v[162:165], v[122:123], off
	v_lshl_add_u64 v[120:121], v[122:123], 0, s[98:99]
	global_load_dwordx4 v[166:169], v[120:121], off
	v_lshl_add_u64 v[122:123], v[120:121], 0, s[98:99]
	global_load_dwordx4 v[170:173], v[122:123], off
	v_lshl_add_u64 v[120:121], v[122:123], 0, s[98:99]
	global_load_dwordx4 v[174:177], v[120:121], off
	v_lshl_add_u64 v[122:123], v[120:121], 0, s[98:99]
	global_load_dwordx4 v[178:181], v[122:123], off
	v_lshl_add_u64 v[120:121], v[122:123], 0, s[98:99]
	global_load_dwordx4 v[182:185], v[120:121], off
	v_lshl_add_u64 v[122:123], v[120:121], 0, s[98:99]
	global_load_dwordx4 v[186:189], v[122:123], off
	v_lshl_add_u64 v[120:121], v[122:123], 0, s[98:99]
	global_load_dwordx4 v[190:193], v[120:121], off
	v_lshl_add_u64 v[122:123], v[120:121], 0, s[98:99]
	global_load_dwordx4 v[194:197], v[122:123], off
	v_lshl_add_u64 v[120:121], v[122:123], 0, s[98:99]
	global_load_dwordx4 v[198:201], v[120:121], off
	v_lshl_add_u64 v[122:123], v[120:121], 0, s[98:99]
	global_load_dwordx4 v[202:205], v[122:123], off
	v_lshl_add_u64 v[120:121], v[122:123], 0, s[98:99]
	global_load_dwordx4 v[206:209], v[120:121], off
	v_lshl_add_u64 v[122:123], v[120:121], 0, s[98:99]
	global_load_dwordx4 v[210:213], v[122:123], off
	v_lshl_add_u64 v[120:121], v[122:123], 0, s[98:99]
	global_load_dwordx4 v[214:217], v[120:121], off
	v_lshl_add_u64 v[122:123], v[120:121], 0, s[98:99]
	global_load_dwordx4 v[218:221], v[122:123], off
	s_add_u32 s26, s26, 0x8000
	s_addc_u32 s27, s27, 0
	v_add_u32_e32 v14, 64, v14
	s_waitcnt vmcnt(15) lgkmcnt(3)
	v_pk_fma_f32 v[6:7], v[160:161], v[136:137], v[6:7] op_sel_hi:[1,0,1]
	v_pk_fma_f32 v[4:5], v[158:159], v[136:137], v[4:5] op_sel_hi:[1,0,1]
	s_waitcnt vmcnt(14)
	v_pk_fma_f32 v[6:7], v[164:165], v[136:137], v[6:7] op_sel:[0,1,0]
	v_pk_fma_f32 v[4:5], v[162:163], v[136:137], v[4:5] op_sel:[0,1,0]
	s_waitcnt vmcnt(13)
	v_pk_fma_f32 v[6:7], v[168:169], v[138:139], v[6:7] op_sel_hi:[1,0,1]
	v_pk_fma_f32 v[4:5], v[166:167], v[138:139], v[4:5] op_sel_hi:[1,0,1]
	s_waitcnt vmcnt(12)
	v_pk_fma_f32 v[6:7], v[172:173], v[138:139], v[6:7] op_sel:[0,1,0]
	v_pk_fma_f32 v[4:5], v[170:171], v[138:139], v[4:5] op_sel:[0,1,0]
	s_waitcnt vmcnt(11) lgkmcnt(2)
	v_pk_fma_f32 v[6:7], v[176:177], v[140:141], v[6:7] op_sel_hi:[1,0,1]
	v_pk_fma_f32 v[4:5], v[174:175], v[140:141], v[4:5] op_sel_hi:[1,0,1]
	s_waitcnt vmcnt(10)
	v_pk_fma_f32 v[6:7], v[180:181], v[140:141], v[6:7] op_sel:[0,1,0]
	v_pk_fma_f32 v[4:5], v[178:179], v[140:141], v[4:5] op_sel:[0,1,0]
	s_waitcnt vmcnt(9)
	v_pk_fma_f32 v[6:7], v[184:185], v[142:143], v[6:7] op_sel_hi:[1,0,1]
	v_pk_fma_f32 v[4:5], v[182:183], v[142:143], v[4:5] op_sel_hi:[1,0,1]
	s_waitcnt vmcnt(8)
	v_pk_fma_f32 v[6:7], v[188:189], v[142:143], v[6:7] op_sel:[0,1,0]
	v_pk_fma_f32 v[4:5], v[186:187], v[142:143], v[4:5] op_sel:[0,1,0]
	s_waitcnt vmcnt(7) lgkmcnt(1)
	v_pk_fma_f32 v[6:7], v[192:193], v[144:145], v[6:7] op_sel_hi:[1,0,1]
	v_pk_fma_f32 v[4:5], v[190:191], v[144:145], v[4:5] op_sel_hi:[1,0,1]
	s_waitcnt vmcnt(6)
	v_pk_fma_f32 v[6:7], v[196:197], v[144:145], v[6:7] op_sel:[0,1,0]
	v_pk_fma_f32 v[4:5], v[194:195], v[144:145], v[4:5] op_sel:[0,1,0]
	s_waitcnt vmcnt(5)
	v_pk_fma_f32 v[6:7], v[200:201], v[146:147], v[6:7] op_sel_hi:[1,0,1]
	v_pk_fma_f32 v[4:5], v[198:199], v[146:147], v[4:5] op_sel_hi:[1,0,1]
	s_waitcnt vmcnt(4)
	v_pk_fma_f32 v[6:7], v[204:205], v[146:147], v[6:7] op_sel:[0,1,0]
	v_pk_fma_f32 v[4:5], v[202:203], v[146:147], v[4:5] op_sel:[0,1,0]
	s_waitcnt vmcnt(3) lgkmcnt(0)
	v_pk_fma_f32 v[6:7], v[208:209], v[148:149], v[6:7] op_sel_hi:[1,0,1]
	v_pk_fma_f32 v[4:5], v[206:207], v[148:149], v[4:5] op_sel_hi:[1,0,1]
	s_waitcnt vmcnt(2)
	v_pk_fma_f32 v[6:7], v[212:213], v[148:149], v[6:7] op_sel:[0,1,0]
	v_pk_fma_f32 v[4:5], v[210:211], v[148:149], v[4:5] op_sel:[0,1,0]
	s_waitcnt vmcnt(1)
	v_pk_fma_f32 v[6:7], v[216:217], v[150:151], v[6:7] op_sel_hi:[1,0,1]
	v_pk_fma_f32 v[4:5], v[214:215], v[150:151], v[4:5] op_sel_hi:[1,0,1]
	s_waitcnt vmcnt(0)
	v_pk_fma_f32 v[6:7], v[220:221], v[150:151], v[6:7] op_sel:[0,1,0]
	v_pk_fma_f32 v[4:5], v[218:219], v[150:151], v[4:5] op_sel:[0,1,0]
	s_cmp_eq_u32 s26, 0x10000
	s_cbranch_scc0 .LBB0_847
	ds_write_b128 v110, v[4:7] offset:14592
	s_waitcnt lgkmcnt(0)
	s_barrier
	s_and_saveexec_b64 s[26:27], s[38:39]
	s_cbranch_execz .LBB0_850
	ds_read2st64_b32 v[0:1], v13 offset0:57 offset1:58
	s_waitcnt lgkmcnt(0)
	v_add_f32_e32 v0, 0, v0
	v_add_f32_e32 v2, v0, v1
	ds_read2st64_b32 v[0:1], v13 offset0:59 offset1:60
	s_waitcnt lgkmcnt(0)
	v_add_f32_e32 v0, v2, v0
	v_add_f32_e32 v2, v0, v1
	ds_read2st64_b32 v[0:1], v13 offset0:61 offset1:62
	s_waitcnt lgkmcnt(0)
	v_add_f32_e32 v0, v2, v0
	v_add_f32_e32 v2, v0, v1
	ds_read2st64_b32 v[0:1], v13 offset0:63 offset1:64
	s_waitcnt lgkmcnt(0)
	v_add_f32_e32 v0, v2, v0
	v_add_f32_e32 v2, v0, v1
	ds_read2st64_b32 v[0:1], v13 offset0:65 offset1:66
	s_waitcnt lgkmcnt(0)
	v_add_f32_e32 v0, v2, v0
	v_add_f32_e32 v2, v0, v1
	ds_read2st64_b32 v[0:1], v13 offset0:67 offset1:68
	s_waitcnt lgkmcnt(0)
	v_add_f32_e32 v0, v2, v0
	v_add_f32_e32 v2, v0, v1
	ds_read2st64_b32 v[0:1], v13 offset0:69 offset1:70
	s_waitcnt lgkmcnt(0)
	v_add_f32_e32 v0, v2, v0
	v_add_f32_e32 v2, v0, v1
	ds_read2st64_b32 v[0:1], v13 offset0:71 offset1:72
	s_waitcnt lgkmcnt(0)
	v_add_f32_e32 v0, v2, v0
	v_add_f32_e32 v2, v0, v1
	ds_read2st64_b32 v[0:1], v13 offset0:73 offset1:74
	s_waitcnt lgkmcnt(0)
	v_add_f32_e32 v0, v2, v0
	v_add_f32_e32 v2, v0, v1
	ds_read2st64_b32 v[0:1], v13 offset0:75 offset1:76
	s_waitcnt lgkmcnt(0)
	v_add_f32_e32 v0, v2, v0
	v_add_f32_e32 v2, v0, v1
	ds_read2st64_b32 v[0:1], v13 offset0:77 offset1:78
	s_waitcnt lgkmcnt(0)
	v_add_f32_e32 v0, v2, v0
	v_add_f32_e32 v2, v0, v1
	ds_read2st64_b32 v[0:1], v13 offset0:79 offset1:80
	s_waitcnt lgkmcnt(0)
	v_add_f32_e32 v0, v2, v0
	v_add_f32_e32 v2, v0, v1
	ds_read2st64_b32 v[0:1], v13 offset0:81 offset1:82
	s_waitcnt lgkmcnt(0)
	v_add_f32_e32 v0, v2, v0
	v_add_f32_e32 v2, v0, v1
	ds_read2st64_b32 v[0:1], v13 offset0:83 offset1:84
	s_waitcnt lgkmcnt(0)
	v_add_f32_e32 v0, v2, v0
	v_add_f32_e32 v2, v0, v1
	ds_read2st64_b32 v[0:1], v13 offset0:85 offset1:86
	s_waitcnt lgkmcnt(0)
	v_add_f32_e32 v0, v2, v0
	v_add_f32_e32 v2, v0, v1
	ds_read2st64_b32 v[0:1], v13 offset0:87 offset1:88
	s_waitcnt lgkmcnt(0)
	v_add_f32_e32 v0, v2, v0
	v_add_f32_e32 v0, v0, v1
	ds_write_b32 v104, v0

; DI unsigned xb_ld(unsigned* p)              { return __hip_atomic_load(p, __ATOMIC_RELAXED, __HIP_MEMORY_SCOPE_AGENT); }
; DI void xcd_barrier_complete(unsigned* bar, unsigned x, unsigned& nloc, unsigned& nx) {
;     ...
;     for (;;) {
;         sum = 0u; cnt = 0u; mine = 0u;
; #pragma unroll
;         for (unsigned j = 0; j < 16; ++j) { const unsigned c = xb_ld(&bar[XB_XCNT(j)]); sum += c; cnt += (c > 0u) ? 1u : 0u; mine = (j == x) ? c : mine; }
;         if (sum == G) break;
;         __builtin_amdgcn_s_sleep(1);
;         if ((++sp & 255u) == 0u) { if (xb_ld(&bar[XB_TMO])) break; if (sp > XB_SPIN_CAP) { atomicAdd(&bar[XB_TMO], 1u); break; } }
;     }
.LBB0_1044:
	v_readlane_b32 s16, v252, 34
	v_readlane_b32 s17, v252, 35
	v_readlane_b32 s18, v253, 61
	s_waitcnt lgkmcnt(0)
	s_nop 2
	global_load_dword v0, v12, s[16:17] sc1
	v_readlane_b32 s16, v252, 36
	v_readlane_b32 s17, v252, 37
	s_nop 4
	global_load_dword v1, v12, s[16:17] sc1
	v_readlane_b32 s16, v252, 38
	v_readlane_b32 s17, v252, 39
	s_nop 4
	global_load_dword v2, v12, s[16:17] sc1
	v_readlane_b32 s16, v252, 40
	v_readlane_b32 s17, v252, 41
	s_nop 4
	global_load_dword v3, v12, s[16:17] sc1
	v_readlane_b32 s16, v252, 42
	v_readlane_b32 s17, v252, 43
	s_nop 4
	global_load_dword v4, v12, s[16:17] sc1
	v_readlane_b32 s16, v252, 44
	v_readlane_b32 s17, v252, 45
	s_nop 4
	global_load_dword v5, v12, s[16:17] sc1
	v_readlane_b32 s16, v252, 46
	v_readlane_b32 s17, v252, 47
	s_nop 4
	global_load_dword v6, v12, s[16:17] sc1
	v_readlane_b32 s16, v252, 48
	v_readlane_b32 s17, v252, 49
	s_nop 4
	global_load_dword v7, v12, s[16:17] sc1
	v_readlane_b32 s16, v252, 50
	v_readlane_b32 s17, v252, 51
	s_nop 4
	global_load_dword v8, v12, s[16:17] sc1
	v_readlane_b32 s16, v252, 52
	v_readlane_b32 s17, v252, 53
	s_nop 4
	global_load_dword v9, v12, s[16:17] sc1
	v_readlane_b32 s16, v252, 54
	v_readlane_b32 s17, v252, 55
	s_nop 4
	global_load_dword v10, v12, s[16:17] sc1
	v_readlane_b32 s16, v252, 56
	v_readlane_b32 s17, v252, 57
	s_nop 4
	global_load_dword v11, v12, s[16:17] sc1
	v_readlane_b32 s16, v252, 58
	v_readlane_b32 s17, v252, 59
	s_nop 4
	global_load_dword v13, v12, s[16:17] sc1
	v_readlane_b32 s16, v252, 60
	v_readlane_b32 s17, v252, 61
	s_nop 4
	global_load_dword v14, v12, s[16:17] sc1
	v_readlane_b32 s16, v252, 62
	v_readlane_b32 s17, v252, 63
	s_nop 4
	global_load_dword v15, v12, s[16:17] sc1
	v_readlane_b32 s16, v253, 0
	v_readlane_b32 s17, v253, 1
	s_nop 4
	global_load_dword v16, v12, s[16:17] sc1
	s_mov_b64 s[16:17], -1
	s_waitcnt vmcnt(0)
	v_add_u32_e32 v17, v1, v0
	v_add_u32_e32 v17, v17, v2
	v_add_u32_e32 v17, v17, v3
	v_add_u32_e32 v17, v17, v4
	v_add_u32_e32 v17, v17, v5
	v_add_u32_e32 v17, v17, v6
	v_add_u32_e32 v17, v17, v7
	v_add_u32_e32 v17, v17, v8
	v_add_u32_e32 v17, v17, v9
	v_add_u32_e32 v17, v17, v10
	v_add_u32_e32 v17, v17, v11
	v_add_u32_e32 v17, v17, v13
	v_add_u32_e32 v17, v17, v14
	v_add_u32_e32 v17, v17, v15
	v_add_u32_e32 v17, v17, v16
	v_cmp_eq_u32_e32 vcc, s18, v17
	s_mov_b64 s[18:19], -1
	s_cbranch_vccnz .LBB0_1043
	s_and_b32 s16, s0, 0xff
	s_cmp_eq_u32 s16, 0
	s_mov_b64 s[16:17], -1
	s_mov_b64 s[22:23], -1
	s_sleep 1
	s_cbranch_scc0 .LBB0_1048
	v_readlane_b32 s16, v252, 32
	v_readlane_b32 s17, v252, 33
	s_nop 4
	global_load_dword v17, v12, s[16:17] sc1
	s_waitcnt vmcnt(0)
	v_cmp_eq_u32_e32 vcc, 0, v17
	s_cbranch_vccnz .LBB0_1050
	s_mov_b64 s[22:23], 0
	s_mov_b64 s[16:17], -1
